# P3 loop: the selection row of an iteration runs before its cmp task, so a drawn row ticket is processed at once (on top of the scalar task-table fetch in P4)
# speedup vs baseline: 1.0023x; 1.0009x over previous
; __global__ void __launch_bounds__(NTHR, 2) fwd_kernel(Args a) {
;     ...
;         for (int i = 0; i < nrow || ci < ncmp; ++i) {
;             if (ci < ncmp && (i >= nrow || (i % stride) == phase)) { const int task = gw + ci * NGW; ++ci;
;                 cmp_task(Z, KCC, VCT, OCMP, SELM, task >> 9, (task >> 8) & 1, (task + 64 * (task >> 11)) & 255, lane); }
;             if (i < nrow) { const int r = gw + i * NGW; select_row(SC, DMASK, r & 15, r >> 4, lane); }
.LBB0_477:
	v_cndmask_b32_e64 v1, 0, 1, s[8:9]
	s_nop 0
	v_cmp_ne_u32_e64 s[76:77], 1, v1
	s_branch .LBB0_535
.Lcmpq:
	s_cmpk_lt_u32 s47, 0x80
	s_cselect_b64 s[8:9], -1, 0
	s_cmp_lt_i32 s63, s58
	s_cselect_b64 s[10:11], -1, 0
	v_cndmask_b32_e64 v1, 0, 1, s[8:9]
	s_andn2_b64 vcc, exec, s[10:11]
	v_cmp_ne_u32_e64 s[76:77], 1, v1
	s_cbranch_vccnz .LBB0_476
	s_and_b64 vcc, exec, s[76:77]
	s_cbranch_vccnz .LBB0_480
	s_mul_hi_u32 s8, s64, s59
	s_mul_i32 s8, s8, s69
	s_sub_i32 s8, s64, s8
	s_sub_i32 s9, s8, s69
	s_cmp_ge_u32 s8, s69
	s_cselect_b32 s8, s9, s8
	s_sub_i32 s9, s8, s69
	s_cmp_ge_u32 s8, s69
	s_cselect_b32 s8, s9, s8
	s_cmp_eq_u32 s8, s60
	s_cselect_b64 s[8:9], -1, 0
	s_andn2_b64 vcc, exec, s[8:9]
	s_cbranch_vccz .LBB0_481
	s_branch .LBB0_476

; __global__ void __launch_bounds__(NTHR, 2) fwd_kernel(Args a) {
;     ...
;             if (ci < ncmp && (i >= nrow || (i % stride) == phase)) { const int task = gw + ci * NGW; ++ci;
;                 cmp_task(Z, KCC, VCT, OCMP, SELM, task >> 9, (task >> 8) & 1, (task + 64 * (task >> 11)) & 255, lane); }
.LBB0_534:
	s_or_b64 exec, exec, s[8:9]
	s_add_i32 s63, s63, 1
	s_branch .LBB0_476
